# P2: tile grid covers only the 65536 latent rows (1536 tiles = 6 full rounds); the context rows K/V columns (their Q is never read) computed as 16x256 strips by all 256 workgroups with direct-from-glob
# baseline (speedup 1.0000x reference)
; #define SEAM(k) do { if (IN(k) && IN((k) + 1)) { if ((k) == 0) cg::this_grid().sync(); else xcd_barrier(xbar); } } while (0)
; #define REP(k) for (int rep_ = 0; rep_ < ((((REPMASK) >> (k)) & 1) ? 2 : 1); ++rep_, (((REPMASK) >> (k)) & 1) ? cg::this_grid().sync() : (void)0)
; __global__ void __launch_bounds__(512, 2) fwd_megakernel(Args a) {
;     ...
;     if (IN(2)) REP(2) { pg8::Gemm g{XN, (const bf16_t*)(ws + WS_WQKV), MT_, NQKV, 1024}; pg8::StaticOrder S; S.init(MT_, NQKV, G, bx);
;         pg8::EpiStoreBf16 E{(bf16_t*)(ws + WS_QKV), (size_t)NQKV, nullptr}; pg8::gemm_phase<pg8::EpiStoreBf16, pg8::StaticOrder, true, true>(L, g, S, E); } SEAM(2);
.LBB0_371:
	s_cmp_lt_i32 s30, 3
	s_cselect_b64 s[4:5], -1, 0
	s_and_b64 s[4:5], s[4:5], s[0:1]
	s_andn2_b64 vcc, exec, s[4:5]
	s_cbranch_vccnz .LBB0_388
	s_cmpk_gt_i32 s2, 0x5ff
	v_readfirstlane_b32 s1, v152
	s_cbranch_scc1 .LBB0_388
	v_and_b32_e32 v8, 15, v152
	v_bfe_u32 v9, v152, 4, 2
	v_lshrrev_b32_e32 v10, 6, v152
	v_mov_b32_e32 v11, s2
	v_lshrrev_b32_e32 v12, 1, v11
	v_and_b32_e32 v13, 1, v11
	v_lshlrev_b32_e32 v12, 4, v12
	v_lshlrev_b32_e32 v13, 8, v13
	v_lshl_add_u32 v13, v10, 5, v13
	v_add_u32_e32 v14, v12, v8
	v_lshlrev_b32_e32 v15, 11, v14
	v_add_u32_e32 v15, 0x8000000, v15
	v_lshl_add_u32 v15, v9, 4, v15
	v_add_u32_e32 v16, v13, v8
	v_lshlrev_b32_e32 v16, 11, v16
	v_add_u32_e32 v16, 0x800000, v16
	v_lshl_add_u32 v4, v9, 4, v16
	v_mul_u32_u24_e32 v18, 0xc00, v14
	v_add_u32_e32 v5, 0x8000, v4
	v_add_u32_e32 v18, 0x1ba00800, v18
	v_lshl_add_u32 v18, v13, 1, v18
	v_lshl_add_u32 v6, v9, 3, v18
	v_mov_b32_e32 v7, v15
	s_nop 1
	global_load_dwordx4 v[16:19], v7, s[16:17]
	global_load_dwordx4 v[20:23], v4, s[28:29]
	global_load_dwordx4 v[24:27], v5, s[28:29]
	global_load_dwordx4 v[28:31], v7, s[16:17] offset:64
	global_load_dwordx4 v[32:35], v4, s[28:29] offset:64
	global_load_dwordx4 v[36:39], v5, s[28:29] offset:64
	global_load_dwordx4 v[40:43], v7, s[16:17] offset:128
	global_load_dwordx4 v[44:47], v4, s[28:29] offset:128
	global_load_dwordx4 v[48:51], v5, s[28:29] offset:128
	global_load_dwordx4 v[52:55], v7, s[16:17] offset:192
	global_load_dwordx4 v[56:59], v4, s[28:29] offset:192
	global_load_dwordx4 v[60:63], v5, s[28:29] offset:192
	global_load_dwordx4 v[64:67], v7, s[16:17] offset:256
	global_load_dwordx4 v[68:71], v4, s[28:29] offset:256
	global_load_dwordx4 v[72:75], v5, s[28:29] offset:256
	global_load_dwordx4 v[76:79], v7, s[16:17] offset:320
	global_load_dwordx4 v[80:83], v4, s[28:29] offset:320
	global_load_dwordx4 v[84:87], v5, s[28:29] offset:320
	global_load_dwordx4 v[88:91], v7, s[16:17] offset:384
	global_load_dwordx4 v[92:95], v4, s[28:29] offset:384
	global_load_dwordx4 v[96:99], v5, s[28:29] offset:384
	global_load_dwordx4 v[100:103], v7, s[16:17] offset:448
	global_load_dwordx4 v[104:107], v4, s[28:29] offset:448
	global_load_dwordx4 v[108:111], v5, s[28:29] offset:448
	global_load_dwordx4 v[112:115], v7, s[16:17] offset:512
	global_load_dwordx4 v[116:119], v4, s[28:29] offset:512
	global_load_dwordx4 v[120:123], v5, s[28:29] offset:512
	global_load_dwordx4 v[124:127], v7, s[16:17] offset:576
	global_load_dwordx4 v[128:131], v4, s[28:29] offset:576
	global_load_dwordx4 v[132:135], v5, s[28:29] offset:576
	global_load_dwordx4 v[136:139], v7, s[16:17] offset:640
	global_load_dwordx4 v[140:143], v4, s[28:29] offset:640
	global_load_dwordx4 v[144:147], v5, s[28:29] offset:640
	global_load_dwordx4 v[148:151], v7, s[16:17] offset:704
	global_load_dwordx4 v[156:159], v4, s[28:29] offset:704
	global_load_dwordx4 v[160:163], v5, s[28:29] offset:704
	global_load_dwordx4 v[164:167], v7, s[16:17] offset:768
	global_load_dwordx4 v[168:171], v4, s[28:29] offset:768
	global_load_dwordx4 v[172:175], v5, s[28:29] offset:768
	global_load_dwordx4 v[176:179], v7, s[16:17] offset:832
	global_load_dwordx4 v[180:183], v4, s[28:29] offset:832
	global_load_dwordx4 v[184:187], v5, s[28:29] offset:832
	global_load_dwordx4 v[188:191], v7, s[16:17] offset:896
	global_load_dwordx4 v[192:195], v4, s[28:29] offset:896
	global_load_dwordx4 v[196:199], v5, s[28:29] offset:896
	global_load_dwordx4 v[200:203], v7, s[16:17] offset:960
	global_load_dwordx4 v[204:207], v4, s[28:29] offset:960
	global_load_dwordx4 v[208:211], v5, s[28:29] offset:960
	s_waitcnt vmcnt(24)
	v_mfma_f32_16x16x32_bf16 v[0:3], v[20:23], v[16:19], 0
	v_mfma_f32_16x16x32_bf16 v[12:15], v[24:27], v[16:19], 0
	v_mfma_f32_16x16x32_bf16 v[0:3], v[32:35], v[28:31], v[0:3]
	v_mfma_f32_16x16x32_bf16 v[12:15], v[36:39], v[28:31], v[12:15]
	v_mfma_f32_16x16x32_bf16 v[0:3], v[44:47], v[40:43], v[0:3]
	v_mfma_f32_16x16x32_bf16 v[12:15], v[48:51], v[40:43], v[12:15]
	v_mfma_f32_16x16x32_bf16 v[0:3], v[56:59], v[52:55], v[0:3]
	v_mfma_f32_16x16x32_bf16 v[12:15], v[60:63], v[52:55], v[12:15]
	v_mfma_f32_16x16x32_bf16 v[0:3], v[68:71], v[64:67], v[0:3]
	v_mfma_f32_16x16x32_bf16 v[12:15], v[72:75], v[64:67], v[12:15]
	v_mfma_f32_16x16x32_bf16 v[0:3], v[80:83], v[76:79], v[0:3]
	v_mfma_f32_16x16x32_bf16 v[12:15], v[84:87], v[76:79], v[12:15]
	v_mfma_f32_16x16x32_bf16 v[0:3], v[92:95], v[88:91], v[0:3]
	v_mfma_f32_16x16x32_bf16 v[12:15], v[96:99], v[88:91], v[12:15]
	v_mfma_f32_16x16x32_bf16 v[0:3], v[104:107], v[100:103], v[0:3]
	v_mfma_f32_16x16x32_bf16 v[12:15], v[108:111], v[100:103], v[12:15]
	global_load_dwordx4 v[16:19], v7, s[16:17] offset:1024
	global_load_dwordx4 v[20:23], v4, s[28:29] offset:1024
	global_load_dwordx4 v[24:27], v5, s[28:29] offset:1024
	global_load_dwordx4 v[28:31], v7, s[16:17] offset:1088
	global_load_dwordx4 v[32:35], v4, s[28:29] offset:1088
	global_load_dwordx4 v[36:39], v5, s[28:29] offset:1088
	global_load_dwordx4 v[40:43], v7, s[16:17] offset:1152
	global_load_dwordx4 v[44:47], v4, s[28:29] offset:1152
	global_load_dwordx4 v[48:51], v5, s[28:29] offset:1152
	global_load_dwordx4 v[52:55], v7, s[16:17] offset:1216
	global_load_dwordx4 v[56:59], v4, s[28:29] offset:1216
	global_load_dwordx4 v[60:63], v5, s[28:29] offset:1216
	global_load_dwordx4 v[64:67], v7, s[16:17] offset:1280
	global_load_dwordx4 v[68:71], v4, s[28:29] offset:1280
	global_load_dwordx4 v[72:75], v5, s[28:29] offset:1280
	global_load_dwordx4 v[76:79], v7, s[16:17] offset:1344
	global_load_dwordx4 v[80:83], v4, s[28:29] offset:1344
	global_load_dwordx4 v[84:87], v5, s[28:29] offset:1344
	global_load_dwordx4 v[88:91], v7, s[16:17] offset:1408
	global_load_dwordx4 v[92:95], v4, s[28:29] offset:1408
	global_load_dwordx4 v[96:99], v5, s[28:29] offset:1408
	global_load_dwordx4 v[100:103], v7, s[16:17] offset:1472
	global_load_dwordx4 v[104:107], v4, s[28:29] offset:1472
	global_load_dwordx4 v[108:111], v5, s[28:29] offset:1472
	s_waitcnt vmcnt(24)
; #define SEAM(k) do { if (IN(k) && IN((k) + 1)) { if ((k) == 0) cg::this_grid().sync(); else xcd_barrier(xbar); } } while (0)
; #define REP(k) for (int rep_ = 0; rep_ < ((((REPMASK) >> (k)) & 1) ? 2 : 1); ++rep_, (((REPMASK) >> (k)) & 1) ? cg::this_grid().sync() : (void)0)
; __global__ void __launch_bounds__(512, 2) fwd_megakernel(Args a) {
;     ...
;     if (IN(2)) REP(2) { pg8::Gemm g{XN, (const bf16_t*)(ws + WS_WQKV), MT_, NQKV, 1024}; pg8::StaticOrder S; S.init(MT_, NQKV, G, bx);
;         pg8::EpiStoreBf16 E{(bf16_t*)(ws + WS_QKV), (size_t)NQKV, nullptr}; pg8::gemm_phase<pg8::EpiStoreBf16, pg8::StaticOrder, true, true>(L, g, S, E); } SEAM(2);
	v_mfma_f32_16x16x32_bf16 v[0:3], v[116:119], v[112:115], v[0:3]
	v_mfma_f32_16x16x32_bf16 v[12:15], v[120:123], v[112:115], v[12:15]
	v_mfma_f32_16x16x32_bf16 v[0:3], v[128:131], v[124:127], v[0:3]
	v_mfma_f32_16x16x32_bf16 v[12:15], v[132:135], v[124:127], v[12:15]
	v_mfma_f32_16x16x32_bf16 v[0:3], v[140:143], v[136:139], v[0:3]
	v_mfma_f32_16x16x32_bf16 v[12:15], v[144:147], v[136:139], v[12:15]
	v_mfma_f32_16x16x32_bf16 v[0:3], v[156:159], v[148:151], v[0:3]
	v_mfma_f32_16x16x32_bf16 v[12:15], v[160:163], v[148:151], v[12:15]
	v_mfma_f32_16x16x32_bf16 v[0:3], v[168:171], v[164:167], v[0:3]
	v_mfma_f32_16x16x32_bf16 v[12:15], v[172:175], v[164:167], v[12:15]
	v_mfma_f32_16x16x32_bf16 v[0:3], v[180:183], v[176:179], v[0:3]
	v_mfma_f32_16x16x32_bf16 v[12:15], v[184:187], v[176:179], v[12:15]
	v_mfma_f32_16x16x32_bf16 v[0:3], v[192:195], v[188:191], v[0:3]
	v_mfma_f32_16x16x32_bf16 v[12:15], v[196:199], v[188:191], v[12:15]
	v_mfma_f32_16x16x32_bf16 v[0:3], v[204:207], v[200:203], v[0:3]
	v_mfma_f32_16x16x32_bf16 v[12:15], v[208:211], v[200:203], v[12:15]
	global_load_dwordx4 v[112:115], v7, s[16:17] offset:1536
	global_load_dwordx4 v[116:119], v4, s[28:29] offset:1536
	global_load_dwordx4 v[120:123], v5, s[28:29] offset:1536
	global_load_dwordx4 v[124:127], v7, s[16:17] offset:1600
	global_load_dwordx4 v[128:131], v4, s[28:29] offset:1600
	global_load_dwordx4 v[132:135], v5, s[28:29] offset:1600
	global_load_dwordx4 v[136:139], v7, s[16:17] offset:1664
	global_load_dwordx4 v[140:143], v4, s[28:29] offset:1664
	global_load_dwordx4 v[144:147], v5, s[28:29] offset:1664
	global_load_dwordx4 v[148:151], v7, s[16:17] offset:1728
	global_load_dwordx4 v[156:159], v4, s[28:29] offset:1728
	global_load_dwordx4 v[160:163], v5, s[28:29] offset:1728
	global_load_dwordx4 v[164:167], v7, s[16:17] offset:1792
	global_load_dwordx4 v[168:171], v4, s[28:29] offset:1792
	global_load_dwordx4 v[172:175], v5, s[28:29] offset:1792
	global_load_dwordx4 v[176:179], v7, s[16:17] offset:1856
	global_load_dwordx4 v[180:183], v4, s[28:29] offset:1856
	global_load_dwordx4 v[184:187], v5, s[28:29] offset:1856
	global_load_dwordx4 v[188:191], v7, s[16:17] offset:1920
	global_load_dwordx4 v[192:195], v4, s[28:29] offset:1920
	global_load_dwordx4 v[196:199], v5, s[28:29] offset:1920
	global_load_dwordx4 v[200:203], v7, s[16:17] offset:1984
	global_load_dwordx4 v[204:207], v4, s[28:29] offset:1984
	global_load_dwordx4 v[208:211], v5, s[28:29] offset:1984
	s_waitcnt vmcnt(24)
	v_mfma_f32_16x16x32_bf16 v[0:3], v[20:23], v[16:19], v[0:3]
	v_mfma_f32_16x16x32_bf16 v[12:15], v[24:27], v[16:19], v[12:15]
	v_mfma_f32_16x16x32_bf16 v[0:3], v[32:35], v[28:31], v[0:3]
	v_mfma_f32_16x16x32_bf16 v[12:15], v[36:39], v[28:31], v[12:15]
	v_mfma_f32_16x16x32_bf16 v[0:3], v[44:47], v[40:43], v[0:3]
	v_mfma_f32_16x16x32_bf16 v[12:15], v[48:51], v[40:43], v[12:15]
	v_mfma_f32_16x16x32_bf16 v[0:3], v[56:59], v[52:55], v[0:3]
	v_mfma_f32_16x16x32_bf16 v[12:15], v[60:63], v[52:55], v[12:15]
	v_mfma_f32_16x16x32_bf16 v[0:3], v[68:71], v[64:67], v[0:3]
	v_mfma_f32_16x16x32_bf16 v[12:15], v[72:75], v[64:67], v[12:15]
	v_mfma_f32_16x16x32_bf16 v[0:3], v[80:83], v[76:79], v[0:3]
	v_mfma_f32_16x16x32_bf16 v[12:15], v[84:87], v[76:79], v[12:15]
	v_mfma_f32_16x16x32_bf16 v[0:3], v[92:95], v[88:91], v[0:3]
	v_mfma_f32_16x16x32_bf16 v[12:15], v[96:99], v[88:91], v[12:15]
	v_mfma_f32_16x16x32_bf16 v[0:3], v[104:107], v[100:103], v[0:3]
	v_mfma_f32_16x16x32_bf16 v[12:15], v[108:111], v[100:103], v[12:15]
	s_waitcnt vmcnt(0)
; #define PG8_STAGE(bufoff, gbase, voff) do { _Pragma("unroll") for (int _i = 0; _i < 2; ++_i) \
;         __builtin_amdgcn_global_load_lds((const unsigned*)((const char*)(gbase) + (voff)[_i]), (PG8_LAS unsigned*)(lds + (bufoff) + ldsw + _i * 8192), 16, 0, 0); } while (0)
; #define PG8_WAIT_V(n) asm volatile("s_waitcnt vmcnt(" #n ")" ::: "memory")
; #define PG8_BAR __builtin_amdgcn_s_barrier()
;     __host__ __device__ bool next(int i, Unit& u) const {
;         const long L = (long)i * G + c; if (L >= nwg) return false;
;         int wgid = (int)L; { const int q = nwg / NXCD, r = nwg % NXCD, xcd = wgid % NXCD, off = wgid / NXCD; wgid = (xcd < r ? xcd * (q + 1) : r * (q + 1) + (xcd - r) * q) + off; }
;         const int nig = WGM * nN, gid = wgid / nig, fm = gid * WGM, gsz = (nM - fm) < WGM ? (nM - fm) : WGM;
;         u.pm = fm + ((wgid % nig) % gsz); u.pn = (wgid % nig) / gsz; return true;
; template <class Epi, class Sched, bool ALIGN_EPI = false, bool SP2 = false>
; __device__ __forceinline__ void gemm_phase(PG8_LAS unsigned char* lds, const Gemm g, const Sched& S, const Epi& E) {
;     ...
;     const char* cA = (const char*)g.A + (size_t)cur.pm * tstep; const char* cB = (const char*)g.Bt + (size_t)cur.pn * tstep;
;     S.a_ready(cur);
;     if constexpr (SP2) {
;         PG8_STAGE(PG8_SB(0, 0), cB, voffB); PG8_STAGE(PG8_SB(0, 1), cB + hstep, voffB); PG8_STAGE(PG8_SA(0, 0), cA, voffA); PG8_STAGE(PG8_SA(0, 1), cA + hstep, voffA);
;         if (wr == 1) PG8_BAR;
;         PG8_WAIT_V(2); PG8_BAR;
;         PG8_STAGE(PG8_SB(1, 0), cB + kstep, voffB); PG8_STAGE(PG8_SA(1, 0), cA + kstep, voffA); PG8_STAGE(PG8_SB(1, 1), cB + hstep + kstep, voffB);
	v_mfma_f32_16x16x32_bf16 v[0:3], v[116:119], v[112:115], v[0:3]
	v_mfma_f32_16x16x32_bf16 v[12:15], v[120:123], v[112:115], v[12:15]
	v_mfma_f32_16x16x32_bf16 v[0:3], v[128:131], v[124:127], v[0:3]
	v_mfma_f32_16x16x32_bf16 v[12:15], v[132:135], v[124:127], v[12:15]
	v_mfma_f32_16x16x32_bf16 v[0:3], v[140:143], v[136:139], v[0:3]
	v_mfma_f32_16x16x32_bf16 v[12:15], v[144:147], v[136:139], v[12:15]
	v_mfma_f32_16x16x32_bf16 v[0:3], v[156:159], v[148:151], v[0:3]
	v_mfma_f32_16x16x32_bf16 v[12:15], v[160:163], v[148:151], v[12:15]
	v_mfma_f32_16x16x32_bf16 v[0:3], v[168:171], v[164:167], v[0:3]
	v_mfma_f32_16x16x32_bf16 v[12:15], v[172:175], v[164:167], v[12:15]
	v_mfma_f32_16x16x32_bf16 v[0:3], v[180:183], v[176:179], v[0:3]
	v_mfma_f32_16x16x32_bf16 v[12:15], v[184:187], v[176:179], v[12:15]
	v_mfma_f32_16x16x32_bf16 v[0:3], v[192:195], v[188:191], v[0:3]
	v_mfma_f32_16x16x32_bf16 v[12:15], v[196:199], v[188:191], v[12:15]
	v_mfma_f32_16x16x32_bf16 v[0:3], v[204:207], v[200:203], v[0:3]
	v_mfma_f32_16x16x32_bf16 v[12:15], v[208:211], v[200:203], v[12:15]
	s_nop 15
	s_nop 3
	v_cvt_pk_bf16_f32 v8, v0, v1
	v_cvt_pk_bf16_f32 v9, v2, v3
	v_cvt_pk_bf16_f32 v10, v12, v13
	v_cvt_pk_bf16_f32 v11, v14, v15
	global_store_dwordx2 v6, v[8:9], s[28:29]
	global_store_dwordx2 v6, v[10:11], s[28:29] offset:32
	s_nop 1
	v_lshrrev_b32_e32 v2, 1, v152
	v_and_b32_e32 v11, 24, v2
	v_lshrrev_b32_e32 v2, 5, v152
	v_and_b32_e32 v2, 4, v2
	v_bfe_u32 v3, v152, 2, 2
	v_lshlrev_b32_e32 v0, 4, v152
	v_and_b32_e32 v1, 32, v152
	v_bfe_u32 v10, v152, 2, 4
	v_or3_b32 v2, v2, v3, v11
	v_lshrrev_b32_e32 v3, 3, v152
	s_movk_i32 s0, 0x70
	v_bitop3_b32 v8, v0, v1, 48 bitop3:0x6c
	v_and_b32_e32 v9, 64, v152
	v_and_or_b32 v4, v3, s0, v10
	s_movk_i32 s0, 0x60
	v_add_u32_e32 v12, 0x2000, v0
	s_add_u32 s52, s28, 0x600000
	v_or_b32_e32 v1, v8, v9
	v_and_or_b32 v3, v3, s0, v2
	v_lshrrev_b32_e32 v0, 7, v12
	s_movk_i32 s0, 0xf0
	s_addc_u32 s53, s29, 0
	v_lshl_or_b32 v130, v3, 11, v1
	v_and_or_b32 v3, v0, s0, v10
	s_movk_i32 s0, 0xe0
	s_ashr_i32 s55, s2, 31
	v_and_or_b32 v0, v0, s0, v2
	s_lshr_b32 s0, s55, 29
	s_add_i32 s0, s2, s0
	s_lshr_b32 s10, s1, 6
	s_ashr_i32 s6, s0, 3
	s_and_b32 s0, s0, -8
	s_lshr_b32 s12, s1, 8
	s_lshl_b32 s54, s10, 10
	s_sub_i32 s0, s2, s0
	s_cmp_lt_i32 s0, 0
	s_movk_i32 s62, 0xc1
	s_cselect_b32 s7, s62, 0xc0
	s_mul_i32 s0, s0, s7
	s_add_i32 s0, s0, s6
	s_mul_hi_i32 s6, s0, 0x2aaaaaab
	s_lshr_b32 s7, s6, 31
	s_ashr_i32 s6, s6, 3
	s_add_i32 s6, s6, s7
	s_lshl_b32 s7, s6, 3
	s_mul_i32 s6, s6, 48
	s_sub_i32 s6, s0, s6
	s_bfe_i32 s0, s6, 0x80000
	s_bfe_u32 s0, s0, 0x3000c
	s_add_i32 s8, s6, s0
	s_bfe_i32 s0, s8, 0x80000
	s_and_b32 s8, s8, 0xf8
	s_sub_i32 s6, s6, s8
	s_sext_i32_i16 s0, s0
	s_sext_i32_i8 s6, s6
	s_lshr_b32 s0, s0, 3
	s_add_i32 s40, s7, s6
	s_ashr_i32 s41, s40, 31
	s_bfe_i64 s[8:9], s[0:1], 0x100000
	s_lshl_b64 s[6:7], s[40:41], 19
	s_lshl_b64 s[8:9], s[8:9], 19
	s_add_u32 s44, s52, s8
	s_addc_u32 s45, s53, s9
	s_add_i32 s41, s54, 0
	s_add_i32 m0, s41, 0x10000
	v_lshl_or_b32 v134, v0, 11, v1
	global_load_lds_dwordx4 v130, s[44:45]
	s_add_i32 m0, s41, 0x12000
	s_add_u32 s8, s44, 0x40000
	global_load_lds_dwordx4 v134, s[44:45]
	s_addc_u32 s9, s45, 0
	s_add_i32 m0, s41, 0x14000
	v_lshl_or_b32 v128, v4, 11, v1
	global_load_lds_dwordx4 v130, s[8:9]
	s_add_i32 m0, s41, 0x16000
	s_add_u32 s42, s16, s6
	s_addc_u32 s43, s17, s7
	s_add_i32 s63, s41, 0x2000
	global_load_lds_dwordx4 v134, s[8:9]
	s_mov_b32 m0, s41
	s_add_u32 s6, s42, 0x40000
	v_lshl_or_b32 v132, v3, 11, v1
	global_load_lds_dwordx4 v128, s[42:43]
	s_mov_b32 m0, s63
	s_addc_u32 s7, s43, 0
	s_add_i32 s70, s41, 0x4000
	global_load_lds_dwordx4 v132, s[42:43]
	s_mov_b32 m0, s70
	s_add_i32 s71, s41, 0x6000
	global_load_lds_dwordx4 v128, s[6:7]
	s_mov_b32 m0, s71
	v_mov_b32_e32 v131, 0
	global_load_lds_dwordx4 v132, s[6:7]
	v_mov_b32_e32 v135, v131
	v_mov_b32_e32 v129, v131
	v_mov_b32_e32 v133, v131
	s_cmp_eq_u32 s12, 1
	s_mov_b32 s72, 0
	v_lshl_add_u64 v[6:7], s[44:45], 0, v[130:131]
	v_lshl_add_u64 v[4:5], s[44:45], 0, v[134:135]
	v_lshl_add_u64 v[0:1], s[42:43], 0, v[128:129]
	s_cselect_b64 s[6:7], -1, 0
	s_cmp_lg_u32 s12, 1
	v_lshl_add_u64 v[2:3], s[42:43], 0, v[132:133]
	s_cbranch_scc1 .LBB0_375
	s_barrier
.LBB0_375:
	s_add_u32 s8, s28, 0xfa00000
	s_addc_u32 s9, s29, 0
	s_lshl_b32 s10, s10, 5
	s_and_b32 s22, s10, 0x60
	s_mov_b64 s[10:11], 0x80
	s_add_i32 m0, s41, 0x18000
	v_lshl_add_u64 v[6:7], v[6:7], 0, s[10:11]
	s_ashr_i32 s73, s3, 31
	s_lshl_b32 s13, s12, 13
	s_lshl_b32 s23, s22, 7
	s_waitcnt vmcnt(2)
	s_barrier
	global_load_lds_dwordx4 v[6:7], off
	v_lshl_add_u64 v[4:5], v[4:5], 0, s[10:11]
	s_add_i32 m0, s41, 0x1a000
	s_add_i32 s74, s41, 0x8000
	s_add_i32 s75, s41, 0xa000
	global_load_lds_dwordx4 v[4:5], off
	v_lshl_add_u64 v[0:1], v[0:1], 0, s[10:11]
	s_mov_b32 m0, s74
	s_add_u32 s20, s44, 0x40080
	global_load_lds_dwordx4 v[0:1], off
	v_lshl_add_u64 v[0:1], v[2:3], 0, s[10:11]
	s_mov_b32 m0, s75
	s_addc_u32 s21, s45, 0
	global_load_lds_dwordx4 v[0:1], off
	s_add_i32 m0, s41, 0x1c000
	v_lshl_add_u64 v[0:1], s[20:21], 0, v[130:131]
	global_load_lds_dwordx4 v[0:1], off
	v_lshl_add_u64 v[0:1], s[20:21], 0, v[134:135]
	s_add_i32 m0, s41, 0x1e000
	s_sext_i32_i8 s79, s0
	global_load_lds_dwordx4 v[0:1], off
	v_and_b32_e32 v0, 15, v152
	v_lshlrev_b32_e32 v1, 1, v11
	v_lshlrev_b32_e32 v2, 6, v152
	s_movk_i32 s0, 0x3c0
	v_lshlrev_b32_e32 v3, 2, v152
	v_and_or_b32 v2, v2, s0, v1
	v_and_b32_e32 v3, 32, v3
	v_lshl_or_b32 v148, s12, 6, v0
	v_lshl_or_b32 v0, v0, 6, v1
	v_lshlrev_b32_e32 v1, 8, v152
	v_bitop3_b32 v149, s23, v2, v3 bitop3:0xf6
	v_and_b32_e32 v1, 0x38000, v1
	v_lshlrev_b32_e32 v2, 11, v10
	v_or3_b32 v1, v8, v1, v2
	v_add_u32_e32 v136, v1, v9
	v_lshlrev_b32_e32 v1, 4, v12
	s_waitcnt vmcnt(6)
	s_cmpk_lt_u32 s1, 0x100
	v_and_b32_e32 v1, 0x78000, v1
	v_bitop3_b32 v0, v0, s13, v3 bitop3:0xde
	s_cselect_b64 s[12:13], -1, 0
	v_or3_b32 v1, v8, v1, v2
	s_add_i32 s76, 0, 0x10000
	s_add_i32 s77, 0, 0x14000
	v_or_b32_e32 v150, s22, v11
	v_mov_b32_e32 v137, v131
	v_add_u32_e32 v138, v1, v9
	v_mov_b32_e32 v139, v131
	v_mov_b64_e32 v[140:141], 0x600
	v_mov_b64_e32 v[142:143], 0x5ff
	v_add_u32_e32 v151, s76, v149
	v_add_u32_e32 v153, s77, v149
	v_add_u32_e32 v154, 0, v0
	s_movk_i32 s78, 0xc00
	s_barrier
	s_mov_b32 s60, 0
	s_branch .LBB0_378

; #define PG8_STAGE(bufoff, gbase, voff) do { _Pragma("unroll") for (int _i = 0; _i < 2; ++_i) \
;         __builtin_amdgcn_global_load_lds((const unsigned*)((const char*)(gbase) + (voff)[_i]), (PG8_LAS unsigned*)(lds + (bufoff) + ldsw + _i * 8192), 16, 0, 0); } while (0)
; #define PG8_LDA(dst, b, h) do { _Pragma("unroll") for (int m = 0; m < 4; ++m) _Pragma("unroll") for (int k = 0; k < 2; ++k) dst[m][k] = *(const PG8_LAS bf16x8*)(lds + PG8_SA(b, h) + aoff + m * 2048 + k * 1024); } while (0)
; #define PG8_LDB(dst, b, h) do { _Pragma("unroll") for (int n = 0; n < 2; ++n) _Pragma("unroll") for (int k = 0; k < 2; ++k) dst[n][k] = *(const PG8_LAS bf16x8*)(lds + PG8_SB(b, h) + boff + n * 2048 + k * 1024); } while (0)
; #define PG8_SCHED __builtin_amdgcn_sched_barrier(0)
;     __host__ __device__ bool next(int i, Unit& u) const {
;         const long L = (long)i * G + c; if (L >= nwg) return false;
;         int wgid = (int)L; { const int q = nwg / NXCD, r = nwg % NXCD, xcd = wgid % NXCD, off = wgid / NXCD; wgid = (xcd < r ? xcd * (q + 1) : r * (q + 1) + (xcd - r) * q) + off; }
;         const int nig = WGM * nN, gid = wgid / nig, fm = gid * WGM, gsz = (nM - fm) < WGM ? (nM - fm) : WGM;
;         u.pm = fm + ((wgid % nig) % gsz); u.pn = (wgid % nig) / gsz; return true;
; template <class Epi, class Sched, bool ALIGN_EPI = false, bool SP2 = false>
; __device__ __forceinline__ void gemm_phase(PG8_LAS unsigned char* lds, const Gemm g, const Sched& S, const Epi& E) {
;     ...
;     for (;;) {
;         const bool has_next = S.next(ui + 1, nxt);
;         const char* nA = has_next ? (const char*)g.A + (size_t)nxt.pm * tstep : cA; const char* nB = has_next ? (const char*)g.Bt + (size_t)nxt.pn * tstep : cB;
;         for (int t = 0; t < nt; t += 2) {
;             const bool last = (t == nt - 2);
;             const char* a1 = cA + (size_t)(t + 1) * kstep;
;             const char* a2 = last ? nA : cA + (size_t)(t + 2) * kstep; const char* b2 = last ? nB : cB + (size_t)(t + 2) * kstep;
;             const char* a3 = a2 + kstep; const char* b3 = b2 + kstep;
;             if (last && has_next) S.a_ready(nxt);
;             if constexpr (SP2) {
;             PG8_LDB(B0, 0, 0); PG8_LDB(B1, 0, 1); PG8_SCHED; PG8_LDA(At, 0, 0); PG8_STAGE(PG8_SA(1, 1), a1 + hstep, voffA);
.LBB0_378:
	ds_read_b128 v[144:147], v151
	ds_read_b128 v[156:159], v151 offset:1024
	ds_read_b128 v[160:163], v151 offset:2048
	ds_read_b128 v[164:167], v151 offset:3072
	ds_read_b128 v[168:171], v153
	ds_read_b128 v[172:175], v153 offset:1024
	ds_read_b128 v[176:179], v153 offset:2048
	ds_read_b128 v[180:183], v153 offset:3072
	ds_read_b128 v[184:187], v154
	ds_read_b128 v[188:191], v154 offset:1024
	ds_read_b128 v[192:195], v154 offset:2048
	ds_read_b128 v[196:199], v154 offset:3072
	ds_read_b128 v[200:203], v154 offset:4096
	ds_read_b128 v[204:207], v154 offset:5120
	ds_read_b128 v[208:211], v154 offset:6144
	ds_read_b128 v[212:215], v154 offset:7168
	s_add_i32 s72, s72, 1
	s_mul_i32 s0, s72, s73
	s_mul_hi_u32 s1, s72, s3
	s_add_i32 s1, s1, s0
	s_mul_i32 s0, s72, s3
	s_add_u32 s24, s0, s2
	s_addc_u32 s25, s1, s55
	v_cmp_gt_i64_e32 vcc, s[24:25], v[142:143]
	v_cmp_lt_i64_e64 s[0:1], s[24:25], v[140:141]
	s_cbranch_vccnz .LBB0_380
	s_ashr_i32 s20, s24, 31
	s_lshr_b32 s20, s20, 29
	s_add_i32 s20, s24, s20
	s_ashr_i32 s21, s20, 3
	s_and_b32 s20, s20, -8
	s_sub_i32 s20, s24, s20
	s_cmp_lt_i32 s20, 0
	s_cselect_b32 s22, s62, 0xc0
	s_mul_i32 s20, s20, s22
	s_add_i32 s20, s20, s21
	s_mul_hi_i32 s21, s20, 0x2aaaaaab
	s_lshr_b32 s22, s21, 31
	s_ashr_i32 s21, s21, 3
	s_add_i32 s21, s21, s22
	s_lshl_b32 s22, s21, 3
	s_sub_i32 s23, 0x100, s22
	s_min_i32 s23, s23, 8
	s_abs_i32 s24, s23
	v_cvt_f32_u32_e32 v0, s24
	s_sub_i32 s33, 0, s24
	s_mul_i32 s21, s21, 48
	s_sub_i32 s21, s20, s21
	v_rcp_iflag_f32_e32 v0, v0
	s_abs_i32 s20, s21
	s_xor_b32 s25, s21, s23
	s_ashr_i32 s25, s25, 31
	v_mul_f32_e32 v0, 0x4f7ffffe, v0
	v_cvt_u32_f32_e32 v0, v0
	s_nop 0
	v_readfirstlane_b32 s34, v0
	s_mul_i32 s33, s33, s34
	s_mul_hi_u32 s33, s34, s33
	s_add_i32 s34, s34, s33
	s_mul_hi_u32 s33, s20, s34
	s_mul_i32 s34, s33, s24
	s_sub_i32 s20, s20, s34
	s_add_i32 s35, s33, 1
	s_sub_i32 s34, s20, s24
	s_cmp_ge_u32 s20, s24
	s_cselect_b32 s33, s35, s33
	s_cselect_b32 s20, s34, s20
	s_add_i32 s34, s33, 1
	s_cmp_ge_u32 s20, s24
	s_cselect_b32 s20, s34, s33
	s_xor_b32 s20, s20, s25
	s_sub_i32 s20, s20, s25
	s_mul_i32 s23, s20, s23
	s_sub_i32 s21, s21, s23
	s_add_i32 s22, s22, s21
